# next-chunk input conversion split over the idle workgroups of two FFN-up tails (layer-1 FFN1-up: own rows, layer-1 FFN2-up: partner rows)
# baseline (speedup 1.0000x reference)
; __global__ void __launch_bounds__(512, 2) mega_fwd(Args args) {
;     ...
;                 const int l = r / 9, k = r - l * 9;
;                 const bf16_t* WL = Wb + (size_t)l * W_LAYER_ELEMS;
;                 if (k == 0 || k == 7) {
;                     pg8::Gemm g{xb, WL + (k == 0 ? OFF_W1IN : OFF_W2IN), TC, 2 * DFF, D, D, D, 0, 0}; pg8::Order S; S.init(TC, 2 * DFF, 1, G, bx); pg8::EpiSwiglu E{hb, DFF}; for (int rep = 0; rep < REP_UP; ++rep) pg8::gemm_phase(lds, g, S, E);
;                     if (c == 0 && l == 0 && k == 0) {
;     ...
;         if (load_chunk >= 0) {
;             const float* xin = load_chunk < 2 ? args.in[0] + (size_t)load_chunk * TC * D : args.in[1] + (size_t)(load_chunk - 2) * TC * D;
;             bf16_t* xnext = (bf16_t*)(ws + ((load_chunk & 1) ? WS_XB : WS_X16));
.LBB0_420:
	s_mov_b32 s22, -1
	s_mov_b32 s100, 0
	v_readlane_b32 s101, v254, 6
	s_nop 1
	s_bitcmp1_b32 s101, 7
	s_cbranch_scc0 .Ltail_no
	v_readlane_b32 s101, v255, 43
	s_nop 1
	s_cmp_eq_u32 s101, 9
	s_cbranch_scc1 .Ltail_yes
	s_cmp_eq_u32 s101, 16
	s_cbranch_scc0 .Ltail_no
	s_addk_i32 s0, 0xff80
.Ltail_yes:
	s_sub_i32 s101, 17, s101
	s_add_i32 s101, s101, s20
	s_mul_hi_u32 s101, s101, 0x38e38e39
	s_lshr_b32 s101, s101, 2
	s_cmp_lt_u32 s101, 4
	s_cselect_b32 s22, s101, -1
